# code placement: .p2align 6 in front of the six GEMM main-loop heads and the three attention tile-loop heads
# baseline (speedup 1.0000x reference)
; template <class Epi, class Sched, bool ALIGN_EPI = false, bool SP2 = false>
; __device__ __forceinline__ void gemm_phase(PG8_LAS unsigned char* lds, const Gemm g, const Sched& S, const Epi& E) {
;     ...
;         const bool has_next = S.next(ui + 1, nxt);
;         const char* nA = has_next ? (const char*)g.A + (size_t)nxt.pm * tstep : cA; const char* nB = has_next ? (const char*)g.Bt + (size_t)nxt.pn * tstep : cB;
;         for (int t = 0; t < nt; t += 2) {
;     ...
; #pragma unroll
;         for (int a = 0; a < 2; ++a)
; #pragma unroll
;             for (int b = 0; b < 2; ++b)
; #pragma unroll
;                 for (int m = 0; m < 4; ++m)
; #pragma unroll
;                     for (int n = 0; n < 2; ++n) acc[a][b][m][n] = (f32x4){0.f, 0.f, 0.f, 0.f};
.LBB0_301:
	s_ashr_i32 s29, s28, 31
	s_lshl_b64 s[8:9], s[28:29], 20
	s_add_u32 s78, s34, s8
	s_addc_u32 s79, s62, s9
	s_and_b64 s[8:9], s[2:3], exec
	s_cselect_b32 s10, s79, s7
	s_cselect_b32 s11, s78, s6
	s_ashr_i32 s1, s0, 31
	s_lshl_b64 s[8:9], s[0:1], 20
	s_add_u32 s88, s63, s8
	s_addc_u32 s89, s54, s9
	s_and_b64 s[8:9], s[2:3], exec
	s_cselect_b32 s1, s89, s5
	s_cselect_b32 s12, s88, s4
	s_add_u32 s13, s4, 0x100
	s_addc_u32 s14, s5, 0
	s_add_u32 s4, s6, 0x80080
	v_mov_b32_e32 v10, 0
	s_addc_u32 s5, s7, 0
	s_mov_b32 s15, -2
	v_mov_b32_e32 v11, v10
	v_mov_b32_e32 v12, v10
	v_mov_b32_e32 v13, v10
	v_mov_b32_e32 v14, v10
	v_mov_b32_e32 v15, v10
	v_mov_b32_e32 v16, v10
	v_mov_b32_e32 v17, v10
	v_mov_b32_e32 v26, v10
	v_mov_b32_e32 v27, v10
	v_mov_b32_e32 v28, v10
	v_mov_b32_e32 v29, v10
	v_mov_b32_e32 v30, v10
	v_mov_b32_e32 v31, v10
	v_mov_b32_e32 v32, v10
	v_mov_b32_e32 v33, v10
	v_mov_b32_e32 v42, v10
	v_mov_b32_e32 v43, v10
	v_mov_b32_e32 v44, v10
	v_mov_b32_e32 v45, v10
	v_mov_b32_e32 v46, v10
	v_mov_b32_e32 v47, v10
	v_mov_b32_e32 v48, v10
	v_mov_b32_e32 v49, v10
	v_mov_b32_e32 v58, v10
	v_mov_b32_e32 v59, v10
	v_mov_b32_e32 v60, v10
	v_mov_b32_e32 v61, v10
	v_mov_b32_e32 v62, v10
	v_mov_b32_e32 v63, v10
	v_mov_b32_e32 v64, v10
	v_mov_b32_e32 v65, v10
	v_mov_b32_e32 v18, v10
	v_mov_b32_e32 v19, v10
	v_mov_b32_e32 v20, v10
	v_mov_b32_e32 v21, v10
	v_mov_b32_e32 v22, v10
	v_mov_b32_e32 v23, v10
	v_mov_b32_e32 v24, v10
	v_mov_b32_e32 v25, v10
	v_mov_b32_e32 v34, v10
	v_mov_b32_e32 v35, v10
	v_mov_b32_e32 v36, v10
	v_mov_b32_e32 v37, v10
	v_mov_b32_e32 v38, v10
	v_mov_b32_e32 v39, v10
	v_mov_b32_e32 v40, v10
	v_mov_b32_e32 v41, v10
	v_mov_b32_e32 v50, v10
	v_mov_b32_e32 v51, v10
	v_mov_b32_e32 v52, v10
	v_mov_b32_e32 v53, v10
	v_mov_b32_e32 v54, v10
	v_mov_b32_e32 v55, v10
	v_mov_b32_e32 v56, v10
	v_mov_b32_e32 v57, v10
	v_mov_b32_e32 v66, v10
	v_mov_b32_e32 v67, v10
	v_mov_b32_e32 v68, v10
	v_mov_b32_e32 v69, v10
	v_mov_b32_e32 v70, v10
	v_mov_b32_e32 v71, v10
	v_mov_b32_e32 v72, v10
	v_mov_b32_e32 v73, v10
	v_mov_b32_e32 v74, v10
	v_mov_b32_e32 v75, v10
	v_mov_b32_e32 v76, v10
	v_mov_b32_e32 v77, v10
	v_mov_b32_e32 v78, v10
	v_mov_b32_e32 v79, v10
	v_mov_b32_e32 v80, v10
	v_mov_b32_e32 v81, v10
	v_mov_b32_e32 v90, v10
	v_mov_b32_e32 v91, v10
	v_mov_b32_e32 v92, v10
	v_mov_b32_e32 v93, v10
	v_mov_b32_e32 v94, v10
	v_mov_b32_e32 v95, v10
	v_mov_b32_e32 v96, v10
	v_mov_b32_e32 v97, v10
	v_mov_b32_e32 v106, v10
	v_mov_b32_e32 v107, v10
	v_mov_b32_e32 v108, v10
	v_mov_b32_e32 v109, v10
	v_mov_b32_e32 v110, v10
	v_mov_b32_e32 v111, v10
	v_mov_b32_e32 v112, v10
	v_mov_b32_e32 v113, v10
	v_mov_b32_e32 v122, v10
	v_mov_b32_e32 v123, v10
	v_mov_b32_e32 v124, v10
	v_mov_b32_e32 v125, v10
	v_mov_b32_e32 v126, v10
	v_mov_b32_e32 v127, v10
	v_mov_b32_e32 v128, v10
	v_mov_b32_e32 v129, v10
	v_mov_b32_e32 v82, v10
	v_mov_b32_e32 v83, v10
	v_mov_b32_e32 v84, v10
	v_mov_b32_e32 v85, v10
	v_mov_b32_e32 v86, v10
	v_mov_b32_e32 v87, v10
	v_mov_b32_e32 v88, v10
	v_mov_b32_e32 v89, v10
	v_mov_b32_e32 v98, v10
	v_mov_b32_e32 v99, v10
	v_mov_b32_e32 v100, v10
	v_mov_b32_e32 v101, v10
	v_mov_b32_e32 v102, v10
	v_mov_b32_e32 v103, v10
	v_mov_b32_e32 v104, v10
	v_mov_b32_e32 v105, v10
	v_mov_b32_e32 v114, v10
	v_mov_b32_e32 v115, v10
	v_mov_b32_e32 v116, v10
	v_mov_b32_e32 v117, v10
	v_mov_b32_e32 v118, v10
	v_mov_b32_e32 v119, v10
	v_mov_b32_e32 v120, v10
	v_mov_b32_e32 v121, v10
	v_mov_b32_e32 v6, v10
	v_mov_b32_e32 v7, v10
	v_mov_b32_e32 v8, v10
	v_mov_b32_e32 v9, v10
	v_mov_b32_e32 v2, v10
	v_mov_b32_e32 v3, v10
	v_mov_b32_e32 v4, v10
	v_mov_b32_e32 v5, v10
	.p2align	6

;     __host__ __device__ bool next(int i, Unit& u) const {
;         const long L = (long)i * G + c; if (L >= nwg) return false;
;         int wgid = (int)L; { const int q = nwg / NXCD, r = nwg % NXCD, xcd = wgid % NXCD, off = wgid / NXCD; wgid = (xcd < r ? xcd * (q + 1) : r * (q + 1) + (xcd - r) * q) + off; }
;         const int nig = WGM * nN, gid = wgid / nig, fm = gid * WGM, gsz = (nM - fm) < WGM ? (nM - fm) : WGM;
;         u.pm = fm + ((wgid % nig) % gsz); u.pn = (wgid % nig) / gsz; return true;
.LBB0_515:
	s_ashr_i32 s10, s12, 3
	s_add_i32 s10, s14, s10
	s_ashr_i32 s11, s10, 31
	s_lshr_b32 s11, s11, 26
	s_add_i32 s11, s10, s11
	s_ashr_i32 s12, s11, 6
	s_lshl_b32 s12, s12, 3
	s_sub_i32 s13, 64, s12
	s_min_i32 s13, s13, 8
	s_abs_i32 s14, s13
	v_cvt_f32_u32_e32 v2, s14
	s_sub_i32 s16, 0, s14
	s_andn2_b32 s11, s11, 63
	s_sub_i32 s11, s10, s11
	v_rcp_iflag_f32_e32 v2, v2
	s_abs_i32 s10, s11
	s_xor_b32 s15, s11, s13
	s_ashr_i32 s15, s15, 31
	v_mul_f32_e32 v2, 0x4f7ffffe, v2
	v_cvt_u32_f32_e32 v2, v2
	s_nop 0
	v_readfirstlane_b32 s17, v2
	s_mul_i32 s16, s16, s17
	s_mul_hi_u32 s16, s17, s16
	s_add_i32 s17, s17, s16
	s_mul_hi_u32 s16, s10, s17
	s_mul_i32 s17, s16, s14
	s_sub_i32 s10, s10, s17
	s_add_i32 s44, s16, 1
	s_sub_i32 s17, s10, s14
	s_cmp_ge_u32 s10, s14
	s_cselect_b32 s16, s44, s16
	s_cselect_b32 s10, s17, s10
	s_add_i32 s17, s16, 1
	s_cmp_ge_u32 s10, s14
	s_cselect_b32 s10, s17, s16
	s_xor_b32 s10, s10, s15
	s_sub_i32 s10, s10, s15
	s_mul_i32 s13, s10, s13
	s_sub_i32 s11, s11, s13
	s_add_i32 s12, s12, s11
	.p2align	6

; template <class Epi, class Sched, bool ALIGN_EPI = false, bool SP2 = false>
; __device__ __forceinline__ void gemm_phase(PG8_LAS unsigned char* lds, const Gemm g, const Sched& S, const Epi& E) {
;     ...
;         const bool has_next = S.next(ui + 1, nxt);
;         const char* nA = has_next ? (const char*)g.A + (size_t)nxt.pm * tstep : cA; const char* nB = has_next ? (const char*)g.Bt + (size_t)nxt.pn * tstep : cB;
;         for (int t = 0; t < nt; t += 2) {
.LBB0_591:
	s_and_b64 vcc, exec, s[2:3]
	s_mov_b64 s[18:19], s[24:25]
	s_cbranch_vccnz .LBB0_593
	s_mul_i32 s18, s48, 0x30000
	s_mul_hi_i32 s19, s48, 0x30000
	s_add_u32 s18, s27, s18
	s_addc_u32 s19, s28, s19
	.p2align	6

;     __host__ __device__ bool next(int i, Unit& u) const {
;         const long L = (long)i * G + c; if (L >= nwg) return false;
;         int wgid = (int)L; { const int q = nwg / NXCD, r = nwg % NXCD, xcd = wgid % NXCD, off = wgid / NXCD; wgid = (xcd < r ? xcd * (q + 1) : r * (q + 1) + (xcd - r) * q) + off; }
;         const int nig = WGM * nN, gid = wgid / nig, fm = gid * WGM, gsz = (nM - fm) < WGM ? (nM - fm) : WGM;
;         u.pm = fm + ((wgid % nig) % gsz); u.pn = (wgid % nig) / gsz; return true;
.LBB0_609:
	v_mov_b64_e32 v[2:3], 0x180
	v_cmp_lt_i64_e64 s[2:3], s[8:9], v[2:3]
	v_mov_b64_e32 v[2:3], 0x17f
	v_cmp_gt_i64_e32 vcc, s[8:9], v[2:3]
	s_cbranch_vccnz .LBB0_611
	s_ashr_i32 s10, s8, 31
	s_lshr_b32 s10, s10, 29
	s_add_i32 s10, s8, s10
	s_ashr_i32 s11, s10, 3
	s_and_b32 s10, s10, -8
	s_sub_i32 s10, s8, s10
	s_cmp_lt_i32 s10, 0
	s_cselect_b32 s12, 49, 48
	s_mul_i32 s10, s12, s10
	s_add_i32 s10, s10, s11
	s_mul_hi_i32 s11, s10, 0x2aaaaaab
	s_lshr_b32 s12, s11, 31
	s_ashr_i32 s11, s11, 3
	s_add_i32 s11, s11, s12
	s_lshl_b32 s12, s11, 3
	s_sub_i32 s13, 64, s12
	s_min_i32 s13, s13, 8
	s_abs_i32 s18, s13
	v_cvt_f32_u32_e32 v0, s18
	s_sub_i32 s22, 0, s18
	s_mul_i32 s11, s11, 48
	s_sub_i32 s11, s10, s11
	v_rcp_iflag_f32_e32 v0, v0
	s_abs_i32 s10, s11
	s_xor_b32 s19, s11, s13
	s_ashr_i32 s19, s19, 31
	v_mul_f32_e32 v0, 0x4f7ffffe, v0
	v_cvt_u32_f32_e32 v0, v0
	s_nop 0
	v_readfirstlane_b32 s23, v0
	s_mul_i32 s22, s22, s23
	s_mul_hi_u32 s22, s23, s22
	s_add_i32 s23, s23, s22
	s_mul_hi_u32 s22, s10, s23
	s_mul_i32 s23, s22, s18
	s_sub_i32 s10, s10, s23
	s_add_i32 s28, s22, 1
	s_sub_i32 s23, s10, s18
	s_cmp_ge_u32 s10, s18
	s_cselect_b32 s22, s28, s22
	s_cselect_b32 s10, s23, s10
	s_add_i32 s23, s22, 1
	s_cmp_ge_u32 s10, s18
	s_cselect_b32 s10, s23, s22
	s_xor_b32 s10, s10, s19
	s_sub_i32 s10, s10, s19
	s_mul_i32 s13, s10, s13
	s_sub_i32 s11, s11, s13
	s_add_i32 s12, s11, s12
	.p2align	6

; template <int MODE>
; __device__ __forceinline__ void attn_unit(LAS char* lds, const AttnPtrs& A, int b, int qb) {
;     ...
;     for (int t = 0; t < NT; ++t) {
;         unsigned mlo = 0, mhi = 0;
;         if constexpr (MODE == 1) { if (t <= cw) {
;             const unsigned long long w = mw_next; mlo = (unsigned)w >> (4 * hi); mhi = (unsigned)(w >> 32) >> (4 * hi);
;             asm volatile("" : "+v"(mlo), "+v"(mhi));
;             if (t < cw) { const unsigned long long* mp_ = A.MASK + qrow * 64 + t + 1; asm volatile("global_load_dwordx2 %0, %1, off" : "+v"(mw_next) : "v"(mp_) : "memory"); } } }
;         const bool more2 = (t + 2 < NT);
;         if (more2) STAGE(t + 2, st_nn);
.LBB0_625:
	s_mul_i32 s26, s16, 0xa000
	v_lshl_add_u64 v[66:67], v[118:119], 0, s[4:5]
	s_add_i32 s26, s9, s26
	v_lshl_add_u64 v[68:69], v[66:67], 0, s[72:73]
	s_mov_b32 m0, s26
	v_lshl_add_u64 v[66:67], v[66:67], 0, s[36:37]
	global_load_lds_dwordx4 v[68:69], off
	v_lshl_add_u64 v[68:69], v[116:117], 0, s[4:5]
	v_lshl_add_u64 v[70:71], v[68:69], 0, s[72:73]
	s_add_i32 m0, s26, 0x400
	s_nop 0
	global_load_lds_dwordx4 v[70:71], off
	s_add_i32 m0, s26, 0x4000
	s_nop 0
	global_load_lds_dwordx4 v[66:67], off
	v_lshl_add_u64 v[66:67], v[68:69], 0, s[36:37]
	s_add_i32 m0, s26, 0x4400
	s_nop 0
	global_load_lds_dwordx4 v[66:67], off
	.p2align	6

; #define LAS __attribute__((address_space(3)))
; template <int MODE>
; __device__ __forceinline__ void attn_unit(LAS char* lds, const AttnPtrs& A, int b, int qb) {
;     constexpr int NQ = (MODE == 0) ? 12 : (MODE == 1 ? 8 : 4);
;     const int tid = opaque_tid(), lane = tid & 63, r32 = lane & 31, hi = lane >> 5, wid = __builtin_amdgcn_readfirstlane(tid >> 6);
;     const int strm = (MODE == 2) ? (wid & 1) : 0;
;     const size_t rowbase = (size_t)b * SEQ; const int q0 = (MODE == 2) ? qb * 128 + (wid >> 1) * 32 : qb * 256 + wid * 32; const int cw = q0 >> 6, NT = (MODE == 2) ? 2 * qb + 2 : 4 * qb + 4;
;     const size_t qrow = rowbase + q0 + r32;
;     const bf16_t* ksrc[2]; const bf16_t* vsrc[2];
; #pragma unroll
;     for (int i = 0; i < 2; ++i) { const unsigned row = 4u * (2 * wid + i) + (lane >> 4), ch = (lane & 15) ^ (((row & 3) << 2) | ((row >> 2) & 3));
;         ksrc[i] = A.K + (rowbase + row) * A.ldk + ch * 8; vsrc[i] = A.V + (rowbase + row) * A.ldv + ch * 8; }
;     const bf16_t* k64src = nullptr;
;     if constexpr (MODE == 0) { const unsigned row = 8u * wid + (lane >> 3), ch = (lane & 7) ^ ((row >> 1) & 7); k64src = A.K64 + (rowbase + row) * 64 + ch * 8; }
;     const unsigned fK = ((r32 & 3) << 2) | ((r32 >> 2) & 3);
;     const unsigned g64 = (r32 >> 1) & 7;
;     const int q4 = (lane & 15) >> 2, p4 = lane & 3, blk = (lane >> 4) & 1;
;     unsigned vrow[2], vlow[2];
; #pragma unroll
;     for (int t = 0; t < 2; ++t) { vrow[t] = 4 * hi + 8 * t + q4; vlow[t] = (unsigned)((2 * blk + (p4 >> 1)) ^ ((hi + 2 * t) & 3)); }
;     ...
;     STAGE(0, 0); STAGE(1, 1);
;     bf16x8 qf[NQ];
; #pragma unroll
;     ...
;                 if (it >= 704) break;
;                 const int qb = 15 - it / 44, w = it % 44;
;                 if (w < 24) { const int b = w / 6, h = w % 6;
;                     att::AttnPtrs A{QMLA + h * 192, NUQ, KMLA + h * 128, 768, KROPE, VMLA + h * 128, 768, GATE + h * 128, GATE + h * 128, nullptr, 0.f, 0.f, (const float*)TAB};
;     ...
;                     att::attn_unit<0>((LAS char*)lds, A, b, qb);
;     ...
;                 } else { const int w2 = w - 24, b = w2 / 5, h = w2 % 5;
;                     att::AttnPtrs A{QKB + h * 128, 1280, QKB + 640 + h * 128, 1280, nullptr, VBC + h * 128, 1280, GATE + 768 + h * 128, GATE + 768 + h * 128, MASK, 0.f, 0.f, nullptr};
;     ...
;                     att::attn_unit<1>((LAS char*)lds, A, b, qb);
.LBB0_1168:
	s_mul_hi_i32 s1, s0, 0xd1745d17
	s_lshr_b32 s12, s1, 31
	s_ashr_i32 s1, s1, 3
	s_add_i32 s49, s1, s12
	s_mul_hi_i32 s1, s0, 0x2e8ba2e9
	s_lshr_b32 s12, s1, 31
	s_ashr_i32 s1, s1, 3
	s_add_i32 s1, s1, s12
	s_mul_i32 s1, s1, 44
	s_add_i32 s49, s49, 15
	s_sub_i32 s14, s0, s1
	s_cmp_gt_i32 s14, 23
	s_mov_b64 s[0:1], -1
	s_cbranch_scc0 .LBB0_1186
	s_add_i32 s0, s14, 0xffe8
	s_and_b32 s12, s0, 0xff
	s_mul_i32 s1, s12, 0xcd
	s_bfe_u32 s13, s1, 0x6000a
	s_mul_i32 s1, s13, 5
	s_sub_i32 s0, s0, s1
	s_and_b32 s0, s0, 0xff
	s_lshl_b32 s15, s0, 7
	s_lshl_b32 s16, s0, 8
	s_add_u32 s0, s21, s16
	s_addc_u32 s1, s22, 0
	s_add_u32 s50, s23, s16
	s_addc_u32 s51, s24, 0
	s_add_u32 s52, s25, s16
	s_getreg_b32 s17, hwreg(HW_REG_HW_ID, 0, 6)
	s_addc_u32 s53, s26, 0
	s_lshl_b32 s17, s17, 2
	s_and_b32 s17, s17, 0xfc
	s_add_i32 s17, s17, 0x20040
	v_mov_b32_e32 v0, s17
	ds_read_b32 v0, v0
	s_lshl_b32 s68, s13, 12
	v_mov_b64_e32 v[6:7], s[50:51]
	v_mov_b32_e32 v3, v1
	s_mul_i32 s13, s13, 0x9ffb00
	s_waitcnt lgkmcnt(0)
	v_readfirstlane_b32 s18, v0
	v_mov_b32_e32 v0, v1
	s_mov_b32 s16, 2
	v_mbcnt_lo_u32_b32 v0, -1, v0
	v_mbcnt_hi_u32_b32 v8, -1, v0
	v_lshl_or_b32 v0, s18, 6, v8
	v_bfe_u32 v9, v8, 4, 2
	v_readfirstlane_b32 s18, v0
	s_ashr_i32 s19, s18, 6
	s_lshl_b32 s18, s49, 8
	s_lshl_b32 s33, s19, 5
	s_add_i32 s54, s33, s18
	s_lshl_b32 s18, s19, 3
	v_or_b32_e32 v0, s18, v9
	s_lshl_b32 s56, s19, 1
	v_and_b32_e32 v13, 15, v8
	v_lshlrev_b32_e32 v20, 2, v9
	s_and_b32 s56, s56, 2
	v_lshl_add_u64 v[4:5], s[68:69], 0, v[0:1]
	v_bitop3_b32 v2, s56, v13, v20 bitop3:0x36
	v_mad_u64_u32 v[10:11], s[50:51], v4, s84, v[6:7]
	v_mad_u32_u24 v11, v5, s84, v11
	v_lshlrev_b32_e32 v2, 4, v2
	v_lshl_add_u64 v[16:17], v[10:11], 0, v[2:3]
	v_mov_b64_e32 v[10:11], s[52:53]
	v_mad_u64_u32 v[14:15], s[50:51], v4, s84, v[10:11]
	s_or_b32 s18, s18, 4
	v_mad_u32_u24 v15, v5, s84, v15
	v_or_b32_e32 v4, s18, v9
	v_mov_b32_e32 v5, v1
	v_lshl_add_u64 v[18:19], v[14:15], 0, v[2:3]
	s_bfe_u32 s18, s18, 0x20002
	v_lshl_add_u64 v[14:15], s[68:69], 0, v[4:5]
	s_lshl_b32 s33, s49, 2
	s_ashr_i32 s55, s54, 31
	v_bitop3_b32 v9, s18, v13, v20 bitop3:0x36
	v_mad_u64_u32 v[6:7], s[50:51], v14, s84, v[6:7]
	v_mad_u64_u32 v[10:11], s[50:51], v14, s84, v[10:11]
	s_ashr_i32 s18, s54, 6
	s_add_u32 s50, s68, s54
	s_addc_u32 s51, 0, s55
	s_lshl_b32 s19, s19, 11
	s_add_i32 s19, s19, 0
	v_mad_u32_u24 v7, v15, s84, v7
	v_lshlrev_b32_e32 v4, 4, v9
	s_mov_b32 m0, s19
	v_lshl_add_u64 v[6:7], v[6:7], 0, v[4:5]
	global_load_lds_dwordx4 v[16:17], off
	s_add_i32 m0, s19, 0x400
	v_mad_u32_u24 v11, v15, s84, v11
	global_load_lds_dwordx4 v[6:7], off
	s_add_i32 m0, s19, 0x4000
	v_lshl_add_u64 v[20:21], v[10:11], 0, v[4:5]
	global_load_lds_dwordx4 v[18:19], off
	s_add_i32 m0, s19, 0x4400
	v_lshl_add_u64 v[16:17], v[16:17], 0, s[60:61]
	global_load_lds_dwordx4 v[20:21], off
	s_add_i32 m0, s19, 0xa000
	v_lshl_add_u64 v[6:7], v[6:7], 0, s[60:61]
	global_load_lds_dwordx4 v[16:17], off
	s_add_i32 m0, s19, 0xa400
	v_and_b32_e32 v12, 31, v8
	global_load_lds_dwordx4 v[6:7], off
	v_lshl_add_u64 v[6:7], v[18:19], 0, s[60:61]
	s_add_i32 m0, s19, 0xe000
	v_or_b32_e32 v130, s50, v12
	global_load_lds_dwordx4 v[6:7], off
	v_lshl_add_u64 v[6:7], v[20:21], 0, s[60:61]
	s_add_i32 m0, s19, 0xe400
	v_bfe_u32 v9, v8, 5, 1
	global_load_lds_dwordx4 v[6:7], off
	v_mov_b64_e32 v[6:7], s[0:1]
	v_mad_u64_u32 v[6:7], s[0:1], v130, s84, v[6:7]
	v_mov_b32_e32 v16, 0xa00
	v_mad_i32_i24 v7, s51, v16, v7
	v_lshlrev_b32_e32 v16, 4, v9
	v_mov_b32_e32 v17, v1
	v_lshl_add_u64 v[6:7], v[6:7], 0, v[16:17]
	global_load_dwordx4 v[98:101], v[6:7], off
	global_load_dwordx4 v[102:105], v[6:7], off offset:32
	global_load_dwordx4 v[106:109], v[6:7], off offset:64
	global_load_dwordx4 v[110:113], v[6:7], off offset:96
	global_load_dwordx4 v[114:117], v[6:7], off offset:128
	global_load_dwordx4 v[118:121], v[6:7], off offset:160
	global_load_dwordx4 v[122:125], v[6:7], off offset:192
	global_load_dwordx4 v[126:129], v[6:7], off offset:224
	v_mov_b32_e32 v131, s51
	v_lshlrev_b64 v[6:7], 9, v[130:131]
	v_lshlrev_b32_e32 v22, 2, v8
	v_lshl_add_u64 v[16:17], s[6:7], 0, v[6:7]
	v_bfe_u32 v23, v8, 2, 2
	v_and_b32_e32 v22, 12, v22
	v_lshlrev_b32_e32 v141, 8, v12
	v_lshlrev_b32_e32 v12, 3, v8
	v_or_b32_e32 v24, v22, v23
	v_lshrrev_b32_e32 v10, 3, v8
	s_waitcnt vmcnt(0)
	global_load_dwordx2 v[132:133], v[16:17], off
	v_mov_b32_e32 v16, 0x4000
	v_and_or_b32 v142, v12, 8, v16
	v_bitop3_b32 v12, v22, v9, v23 bitop3:0x36
	v_lshlrev_b32_e32 v143, 4, v12
	v_bitop3_b32 v12, v9, v24, 2 bitop3:0x36
	v_lshlrev_b32_e32 v144, 4, v12
	v_bitop3_b32 v12, v9, v24, 4 bitop3:0x36
	v_lshlrev_b32_e32 v145, 4, v12
	v_bitop3_b32 v12, v9, v24, 6 bitop3:0x36
	v_lshlrev_b32_e32 v146, 4, v12
	v_bitop3_b32 v12, v9, v24, 8 bitop3:0x36
	v_lshlrev_b32_e32 v147, 4, v12
	v_bitop3_b32 v12, v9, v24, 10 bitop3:0x36
	v_and_b32_e32 v11, 2, v10
	v_bfe_u32 v13, v8, 1, 1
	v_lshlrev_b32_e32 v148, 4, v12
	v_bitop3_b32 v12, v9, v24, 12 bitop3:0x36
	v_lshlrev_b32_e32 v140, 2, v9
	v_or_b32_e32 v10, v13, v11
	v_lshlrev_b32_e32 v149, 4, v12
	v_bitop3_b32 v12, v9, v24, 14 bitop3:0x36
	v_or_b32_e32 v14, v140, v23
	v_bitop3_b32 v15, v13, v9, v11 bitop3:0x36
	v_bitop3_b32 v13, v9, v10, 2 bitop3:0x36
	v_lshlrev_b32_e32 v150, 4, v12
	v_and_b32_e32 v12, 12, v8
	v_lshlrev_b32_e32 v151, 8, v14
	v_or_b32_e32 v14, v15, v12
	v_or_b32_e32 v12, v13, v12
	v_or_b32_e32 v11, 2, v9
	v_lshlrev_b32_e32 v154, 4, v12
	v_bitop3_b32 v12, v8, 4, 12 bitop3:0x6c
	s_mov_b64 s[0:1], 0x2d990000
	s_add_i32 s33, s33, 4
	v_bitop3_b32 v13, v10, v12, v9 bitop3:0xde
	v_bitop3_b32 v12, v11, v12, v10 bitop3:0xde
	v_lshl_add_u64 v[134:135], v[6:7], 0, s[0:1]
	s_lshl_b32 s0, s12, 8
	v_lshlrev_b32_e32 v178, 4, v12
	v_bitop3_b32 v12, v8, 8, 12 bitop3:0x6c
	v_bitop3_b32 v8, v8, 12, v8 bitop3:0xc
	s_add_u32 s0, s0, s13
	v_lshlrev_b32_e32 v177, 4, v13
	v_bitop3_b32 v13, v10, v12, v9 bitop3:0xde
	v_bitop3_b32 v9, v10, v8, v9 bitop3:0xde
	v_bitop3_b32 v8, v11, v8, v10 bitop3:0xde
	s_addc_u32 s1, 0, 0
	v_lshlrev_b32_e32 v182, 4, v8
	v_or_b32_e32 v8, 4, v0
	v_mov_b64_e32 v[6:7], s[0:1]
	v_lshlrev_b32_e32 v181, 4, v9
	v_mad_u64_u32 v[8:9], s[0:1], v8, s84, v[6:7]
	v_lshlrev_b32_e32 v152, 4, v14
	v_bitop3_b32 v12, v11, v12, v10 bitop3:0xde
	v_lshl_add_u64 v[136:137], v[8:9], 0, v[4:5]
	v_mad_u64_u32 v[4:5], s[0:1], v0, s84, v[6:7]
	v_mov_b32_e32 v14, v1
	v_mov_b32_e32 v15, v1
	s_waitcnt vmcnt(0)
	s_waitcnt vmcnt(0) lgkmcnt(0)
	s_barrier
; #define WAIT_TILE(all_) do { if (all_) asm volatile("s_waitcnt vmcnt(0) lgkmcnt(0)" ::: "memory"); \
;         else if constexpr (MODE == 0) asm volatile("s_waitcnt vmcnt(5) lgkmcnt(0)" ::: "memory"); else asm volatile("s_waitcnt vmcnt(4) lgkmcnt(0)" ::: "memory"); \
;         __builtin_amdgcn_s_barrier(); asm volatile("" ::: "memory"); } while (0)
; template <int MODE>
; __device__ __forceinline__ void attn_unit(LAS char* lds, const AttnPtrs& A, int b, int qb) {
;     ...
;     f32x16 o1[4];
; #pragma unroll
;     for (int c = 0; c < 4; ++c) o1[c] = f32x16{};
;     float m1 = -1e30f, l1 = 0.f;
;     unsigned long long mw_next = 0ull;
;     if constexpr (MODE == 1) { mw_next = A.MASK[qrow * 64]; asm volatile("" : "+v"(mw_next)); }
;     bf16x8 pk[4]; float a1 = 1.f;
;     ...
;     WAIT_TILE(true);
;     int st_cur = 0, st_nn = 2;
;     for (int t = 0; t < NT; ++t) {
;         unsigned mlo = 0, mhi = 0;
;         if constexpr (MODE == 1) { if (t <= cw) {
	v_lshlrev_b32_e32 v179, 4, v13
	v_lshlrev_b32_e32 v180, 4, v12
	v_lshl_add_u64 v[138:139], v[4:5], 0, v[2:3]
	v_mov_b32_e32 v0, v1
	v_mov_b32_e32 v2, v1
	v_mov_b32_e32 v4, v1
	v_mov_b32_e32 v5, v1
	v_mov_b32_e32 v6, v1
	v_mov_b32_e32 v7, v1
	v_mov_b32_e32 v8, v1
	v_mov_b32_e32 v9, v1
	v_mov_b32_e32 v10, v1
	v_mov_b32_e32 v11, v1
	v_mov_b32_e32 v12, v1
	v_mov_b32_e32 v13, v1
	v_mov_b64_e32 v[64:65], v[14:15]
	v_mov_b64_e32 v[48:49], v[14:15]
	v_mov_b64_e32 v[32:33], v[14:15]
	v_mov_b64_e32 v[62:63], v[12:13]
	v_mov_b64_e32 v[60:61], v[10:11]
	v_mov_b64_e32 v[58:59], v[8:9]
	v_mov_b64_e32 v[56:57], v[6:7]
	v_mov_b64_e32 v[54:55], v[4:5]
	v_mov_b64_e32 v[52:53], v[2:3]
	v_mov_b64_e32 v[50:51], v[0:1]
	v_mov_b64_e32 v[46:47], v[12:13]
	v_mov_b64_e32 v[44:45], v[10:11]
	v_mov_b64_e32 v[42:43], v[8:9]
	v_mov_b64_e32 v[40:41], v[6:7]
	v_mov_b64_e32 v[38:39], v[4:5]
	v_mov_b64_e32 v[36:37], v[2:3]
	v_mov_b64_e32 v[34:35], v[0:1]
	v_mov_b64_e32 v[30:31], v[12:13]
	v_mov_b64_e32 v[28:29], v[10:11]
	v_mov_b64_e32 v[26:27], v[8:9]
	v_mov_b64_e32 v[24:25], v[6:7]
	v_mov_b64_e32 v[22:23], v[4:5]
	v_mov_b64_e32 v[20:21], v[2:3]
	v_mov_b64_e32 v[18:19], v[0:1]
	v_mov_b64_e32 v[16:17], v[14:15]
	s_mov_b32 s17, 0
	v_or_b32_e32 v153, 0x800, v151
	v_or_b32_e32 v155, 0x1000, v151
	v_or_b32_e32 v156, 0x1800, v151
	v_or_b32_e32 v157, 0x2000, v151
	v_or_b32_e32 v158, 0x2800, v151
	v_or_b32_e32 v159, 0x3000, v151
	v_or_b32_e32 v176, 0x3800, v151
	v_mov_b32_e32 v184, 0xf149f2ca
	v_mov_b32_e32 v253, s97
	v_mov_b32_e32 v252, 0
	v_mov_b64_e32 v[236:237], 0
	v_mov_b64_e32 v[238:239], 0
	v_mov_b64_e32 v[240:241], 0
	v_mov_b64_e32 v[242:243], 0
	v_mov_b64_e32 v[244:245], 0
	v_mov_b64_e32 v[246:247], 0
	v_mov_b64_e32 v[248:249], 0
	v_mov_b64_e32 v[250:251], 0
	v_mov_b32_e32 v183, 0
	v_mov_b64_e32 v[14:15], v[12:13]
	v_mov_b64_e32 v[12:13], v[10:11]
	v_mov_b64_e32 v[10:11], v[8:9]
	v_mov_b64_e32 v[8:9], v[6:7]
	v_mov_b64_e32 v[6:7], v[4:5]
	v_mov_b64_e32 v[4:5], v[2:3]
	v_mov_b64_e32 v[2:3], v[0:1]
	s_mov_b32 s50, 0
	s_cmp_le_i32 s50, s18
	s_cselect_b64 s[12:13], -1, 0
	s_cmp_gt_i32 s50, s18
	s_cbranch_scc1 .LBB0_1171
	s_branch .LBB0_1172
	.p2align	6

; #define LAS __attribute__((address_space(3)))
; template <int MODE>
; __device__ __forceinline__ void attn_unit(LAS char* lds, const AttnPtrs& A, int b, int qb) {
;     constexpr int NQ = (MODE == 0) ? 12 : (MODE == 1 ? 8 : 4);
;     const int tid = opaque_tid(), lane = tid & 63, r32 = lane & 31, hi = lane >> 5, wid = __builtin_amdgcn_readfirstlane(tid >> 6);
;     const int strm = (MODE == 2) ? (wid & 1) : 0;
;     const size_t rowbase = (size_t)b * SEQ; const int q0 = (MODE == 2) ? qb * 128 + (wid >> 1) * 32 : qb * 256 + wid * 32; const int cw = q0 >> 6, NT = (MODE == 2) ? 2 * qb + 2 : 4 * qb + 4;
;     const size_t qrow = rowbase + q0 + r32;
;     const bf16_t* ksrc[2]; const bf16_t* vsrc[2];
; #pragma unroll
;     for (int i = 0; i < 2; ++i) { const unsigned row = 4u * (2 * wid + i) + (lane >> 4), ch = (lane & 15) ^ (((row & 3) << 2) | ((row >> 2) & 3));
;         ksrc[i] = A.K + (rowbase + row) * A.ldk + ch * 8; vsrc[i] = A.V + (rowbase + row) * A.ldv + ch * 8; }
;     const bf16_t* k64src = nullptr;
;     if constexpr (MODE == 0) { const unsigned row = 8u * wid + (lane >> 3), ch = (lane & 7) ^ ((row >> 1) & 7); k64src = A.K64 + (rowbase + row) * 64 + ch * 8; }
;     const unsigned fK = ((r32 & 3) << 2) | ((r32 >> 2) & 3);
;     const unsigned g64 = (r32 >> 1) & 7;
;     const int q4 = (lane & 15) >> 2, p4 = lane & 3, blk = (lane >> 4) & 1;
;     unsigned vrow[2], vlow[2];
; #pragma unroll
;     for (int t = 0; t < 2; ++t) { vrow[t] = 4 * hi + 8 * t + q4; vlow[t] = (unsigned)((2 * blk + (p4 >> 1)) ^ ((hi + 2 * t) & 3)); }
;     ...
;     STAGE(0, 0); STAGE(1, 1);
;     bf16x8 qf[NQ];
; #pragma unroll
;     for (int s = 0; s < NQ; ++s) qf[s] = *(const bf16x8*)(A.Q + qrow * A.ldq + 64 * strm + 16 * s + 8 * hi);
;     if constexpr (MODE == 0) {
; #pragma unroll
;         for (int s = 0; s < 4; ++s) {
;             const u32x4 w = __builtin_bit_cast(u32x4, qf[8 + s]);
;             const f32x4 t0 = *(const f32x4*)(A.subg + (qrow * 56 + 8 * s + 4 * hi) * 2), t1 = *(const f32x4*)(A.subg + (qrow * 56 + 8 * s + 4 * hi) * 2 + 4);
;             u32x4 o;
;     ...
;                 if (w < 24) { const int b = w / 6, h = w % 6;
;                     att::AttnPtrs A{QMLA + h * 192, NUQ, KMLA + h * 128, 768, KROPE, VMLA + h * 128, 768, GATE + h * 128, GATE + h * 128, nullptr, 0.f, 0.f, (const float*)TAB};
;     ...
;                     att::attn_unit<0>((LAS char*)lds, A, b, qb);
.LBB0_1186:
	s_and_b64 vcc, exec, s[0:1]
	s_cbranch_vccz .LBB0_1201
	s_bfe_i32 s0, s14, 0x80000
	s_mul_i32 s0, s0, 43
	s_bfe_u32 s1, s0, 0x1000f
	s_bfe_u32 s0, s0, 0x80008
	s_add_i32 s12, s0, s1
	s_mul_i32 s0, s12, 6
	s_sub_i32 s0, s14, s0
	s_sext_i32_i8 s13, s0
	s_mul_i32 s0, s13, 0xc0
	s_ashr_i32 s1, s0, 31
	s_lshl_b64 s[0:1], s[0:1], 1
	s_add_u32 s16, s29, s0
	s_addc_u32 s17, s34, s1
	s_lshl_b32 s0, s13, 7
	s_ashr_i32 s1, s0, 31
	s_lshl_b64 s[0:1], s[0:1], 1
	s_add_u32 s52, s35, s0
	s_addc_u32 s53, s44, s1
	s_add_u32 s54, s45, s0
	s_getreg_b32 s13, hwreg(HW_REG_HW_ID, 0, 6)
	s_addc_u32 s55, s46, s1
	s_lshl_b32 s13, s13, 2
	s_and_b32 s13, s13, 0xfc
	s_add_i32 s13, s13, 0x20040
	v_mov_b32_e32 v0, s13
	ds_read_b32 v0, v0
	s_lshl_b32 s51, s49, 8
	v_mov_b64_e32 v[6:7], s[52:53]
	v_mov_b32_e32 v3, v1
	s_mov_b32 s33, 2
	s_waitcnt lgkmcnt(0)
	v_readfirstlane_b32 s13, v0
	v_mov_b32_e32 v0, v1
	s_mov_b32 s50, 0
	v_mbcnt_lo_u32_b32 v0, -1, v0
	v_mbcnt_hi_u32_b32 v8, -1, v0
	v_lshl_or_b32 v11, s13, 6, v8
	v_bfe_u32 v10, v8, 4, 2
	v_readfirstlane_b32 s13, v11
	s_ashr_i32 s13, s13, 6
	s_bfe_i64 s[14:15], s[12:13], 0x80000
	s_lshl_b32 s56, s13, 5
	s_lshl_b32 s58, s13, 3
	s_lshl_b64 s[18:19], s[14:15], 12
	s_add_i32 s56, s56, s51
	s_lshl_b32 s51, s49, 2
	v_or_b32_e32 v0, s58, v10
	s_lshl_b32 s49, s13, 1
	v_and_b32_e32 v16, 15, v8
	v_lshlrev_b32_e32 v17, 2, v10
	s_and_b32 s49, s49, 2
	v_lshl_add_u64 v[4:5], s[18:19], 0, v[0:1]
	v_bitop3_b32 v2, s49, v16, v17 bitop3:0x36
	v_mad_u64_u32 v[12:13], s[52:53], v4, s20, v[6:7]
	v_mad_i32_i24 v13, v5, s20, v13
	v_lshlrev_b32_e32 v2, 4, v2
	v_lshl_add_u64 v[38:39], v[12:13], 0, v[2:3]
	v_mov_b64_e32 v[12:13], s[54:55]
	v_mad_u64_u32 v[14:15], s[52:53], v4, s20, v[12:13]
	s_or_b32 s49, s58, 4
	v_mad_i32_i24 v15, v5, s20, v15
	v_or_b32_e32 v4, s49, v10
	v_mov_b32_e32 v5, v1
	v_lshl_add_u64 v[40:41], v[14:15], 0, v[2:3]
	s_bfe_u32 s49, s49, 0x20002
	v_lshl_add_u64 v[14:15], s[18:19], 0, v[4:5]
	v_bitop3_b32 v10, s49, v16, v17 bitop3:0x36
	v_mad_u64_u32 v[6:7], s[52:53], v14, s20, v[6:7]
	v_mad_i32_i24 v7, v15, s20, v7
	v_lshlrev_b32_e32 v4, 4, v10
	s_ashr_i32 s57, s56, 31
	v_lshl_add_u64 v[42:43], v[6:7], 0, v[4:5]
	v_mad_u64_u32 v[6:7], s[52:53], v14, s20, v[12:13]
	s_ashr_i32 s49, s56, 6
	v_and_b32_e32 v9, 31, v8
	s_add_u32 s52, s18, s56
	v_mad_i32_i24 v7, v15, s20, v7
	v_or_b32_e32 v178, s52, v9
	v_mov_b64_e32 v[14:15], s[16:17]
	s_movk_i32 s16, 0x900
	v_mad_u64_u32 v[14:15], s[16:17], v178, s16, v[14:15]
	v_mad_u64_u32 v[18:19], s[16:17], v178, 56, 0
	v_lshl_add_u64 v[50:51], v[6:7], 0, v[4:5]
	v_bfe_u32 v12, v8, 5, 1
	s_addc_u32 s53, s19, s57
	v_mov_b32_e32 v7, 0x900
	v_mov_b32_e32 v20, v19
	v_lshlrev_b32_e32 v176, 2, v12
	v_mad_i32_i24 v15, s53, v7, v15
	v_lshlrev_b32_e32 v16, 4, v12
	v_mov_b32_e32 v17, v1
	v_mad_u64_u32 v[20:21], s[16:17], s53, 56, v[20:21]
	v_lshl_add_u64 v[52:53], v[14:15], 0, v[16:17]
	v_or_b32_e32 v18, v18, v176
	v_mov_b32_e32 v19, v20
	global_load_dwordx4 v[14:17], v[52:53], off offset:256
	v_lshl_add_u64 v[58:59], v[18:19], 3, s[10:11]
	global_load_dwordx4 v[18:21], v[58:59], off offset:16
	global_load_dwordx4 v[22:25], v[58:59], off
	v_bfe_u32 v6, v8, 3, 3
	v_or_b32_e32 v6, s58, v6
	v_lshrrev_b32_e32 v10, 1, v6
	v_mov_b32_e32 v7, v1
	s_lshl_b32 s16, s13, 11
	v_xor_b32_e32 v13, v10, v8
	v_lshl_add_u64 v[26:27], s[18:19], 0, v[6:7]
	v_lshrrev_b32_e32 v28, 3, v8
	s_add_i32 s16, s16, 0
	v_lshlrev_b64 v[26:27], 7, v[26:27]
	v_and_b32_e32 v28, 2, v28
	v_bfe_u32 v29, v11, 1, 1
	v_or_b32_e32 v67, 2, v12
	v_lshlrev_b32_e32 v13, 4, v13
	s_mov_b32 m0, s16
	v_lshlrev_b32_e32 v30, 2, v8
	v_or_b32_e32 v64, v29, v28
	v_bitop3_b32 v66, v29, v12, v28 bitop3:0x36
	v_bitop3_b32 v68, v29, v67, v28 bitop3:0x36
	v_lshl_add_u64 v[26:27], s[8:9], 0, v[26:27]
	v_and_b32_e32 v28, 0x70, v13
	v_mov_b32_e32 v29, v1
	global_load_lds_dwordx4 v[38:39], off
	v_lshl_add_u64 v[54:55], v[26:27], 0, v[28:29]
	v_and_b32_e32 v13, 12, v30
	global_load_dwordx4 v[26:29], v[52:53], off offset:288
	global_load_dwordx4 v[30:33], v[58:59], off offset:80
	global_load_dwordx4 v[34:37], v[58:59], off offset:64
	s_add_i32 m0, s16, 0x400
	s_lshl_b32 s13, s13, 10
	global_load_lds_dwordx4 v[42:43], off
	s_add_i32 m0, s16, 0x4000
	s_sub_i32 s17, s16, s13
	global_load_lds_dwordx4 v[40:41], off
	s_add_i32 m0, s16, 0x4400
	v_lshl_add_u64 v[38:39], v[38:39], 0, s[94:95]
	global_load_lds_dwordx4 v[50:51], off
	s_add_i32 m0, s17, 0x8000
	v_lshl_add_u64 v[56:57], v[40:41], 0, s[94:95]
	global_load_lds_dwordx4 v[54:55], off
	s_add_i32 m0, s16, 0xa000
	v_lshl_add_u64 v[50:51], v[50:51], 0, s[94:95]
	global_load_lds_dwordx4 v[38:39], off
	v_lshl_add_u64 v[38:39], v[42:43], 0, s[94:95]
	s_add_i32 m0, s16, 0xa400
	v_bfe_u32 v62, v8, 2, 2
	global_load_lds_dwordx4 v[38:39], off
	global_load_dwordx4 v[38:41], v[52:53], off offset:320
	s_nop 0
	global_load_dwordx4 v[42:45], v[58:59], off offset:144
	global_load_dwordx4 v[46:49], v[58:59], off offset:128
	s_add_i32 m0, s16, 0xe000
	v_lshlrev_b32_e32 v177, 7, v9
	global_load_lds_dwordx4 v[56:57], off
	s_add_i32 m0, s16, 0xe400
	v_lshlrev_b32_e32 v186, 8, v9
	global_load_lds_dwordx4 v[50:51], off
	v_lshl_add_u64 v[50:51], v[54:55], 0, s[38:39]
	s_add_i32 m0, s17, 0x12000
	v_lshlrev_b32_e32 v9, 3, v8
	global_load_lds_dwordx4 v[50:51], off
	global_load_dwordx4 v[112:115], v[52:53], off
	global_load_dwordx4 v[116:119], v[52:53], off offset:32
	global_load_dwordx4 v[120:123], v[52:53], off offset:64
	global_load_dwordx4 v[124:127], v[52:53], off offset:96
	global_load_dwordx4 v[128:131], v[52:53], off offset:128
	global_load_dwordx4 v[132:135], v[52:53], off offset:160
	global_load_dwordx4 v[136:139], v[52:53], off offset:192
	global_load_dwordx4 v[140:143], v[52:53], off offset:224
	s_nop 0
	global_load_dwordx4 v[50:53], v[52:53], off offset:352
	v_or_b32_e32 v69, v13, v62
	v_lshrrev_b32_e32 v63, 1, v11
	v_bfe_u32 v11, v11, 1, 3
	s_add_i32 s17, s51, 4
	s_add_i32 s18, s13, 0
	s_lshl_b64 s[14:15], s[14:15], 19
	s_add_u32 s14, s14, 0x1b914000
	s_addc_u32 s15, s15, 0
	v_lshlrev_b64 v[6:7], 7, v[6:7]
	v_lshl_add_u64 v[180:181], s[14:15], 0, v[6:7]
	s_waitcnt vmcnt(0)
; __device__ __forceinline__ unsigned cvtpk(float lo, float hi) { unsigned r; asm("v_cvt_pk_bf16_f32 %0, %1, %2" : "=v"(r) : "v"(lo), "v"(hi)); return r; }
; __device__ __forceinline__ float bf_lo(unsigned w) { return __uint_as_float(w << 16); }
; __device__ __forceinline__ float bf_hi(unsigned w) { return __uint_as_float(w & 0xffff0000u); }
; template <int MODE>
; __device__ __forceinline__ void attn_unit(LAS char* lds, const AttnPtrs& A, int b, int qb) {
;     ...
;     const unsigned fK = ((r32 & 3) << 2) | ((r32 >> 2) & 3);
;     const unsigned g64 = (r32 >> 1) & 7;
;     const int q4 = (lane & 15) >> 2, p4 = lane & 3, blk = (lane >> 4) & 1;
;     unsigned vrow[2], vlow[2];
; #pragma unroll
;     for (int t = 0; t < 2; ++t) { vrow[t] = 4 * hi + 8 * t + q4; vlow[t] = (unsigned)((2 * blk + (p4 >> 1)) ^ ((hi + 2 * t) & 3)); }
;     ...
;     STAGE(0, 0); STAGE(1, 1);
;     bf16x8 qf[NQ];
; #pragma unroll
;     for (int s = 0; s < NQ; ++s) qf[s] = *(const bf16x8*)(A.Q + qrow * A.ldq + 64 * strm + 16 * s + 8 * hi);
;     if constexpr (MODE == 0) {
; #pragma unroll
;         for (int s = 0; s < 4; ++s) {
;             const u32x4 w = __builtin_bit_cast(u32x4, qf[8 + s]);
;             const f32x4 t0 = *(const f32x4*)(A.subg + (qrow * 56 + 8 * s + 4 * hi) * 2), t1 = *(const f32x4*)(A.subg + (qrow * 56 + 8 * s + 4 * hi) * 2 + 4);
;             u32x4 o;
;             { const float a = bf_lo(w.x), b = bf_hi(w.x); o.x = cvtpk(a * t0[0] - b * t0[1], b * t0[0] + a * t0[1]); }
;             { const float a = bf_lo(w.y), b = bf_hi(w.y); o.y = cvtpk(a * t0[2] - b * t0[3], b * t0[2] + a * t0[3]); }
;             { const float a = bf_lo(w.z), b = bf_hi(w.z); o.z = cvtpk(a * t1[0] - b * t1[1], b * t1[0] + a * t1[1]); }
;             { const float a = bf_lo(w.w), b = bf_hi(w.w); o.w = cvtpk(a * t1[2] - b * t1[3], b * t1[2] + a * t1[3]); }
;             qf[8 + s] = __builtin_bit_cast(bf16x8, o);
;         }
;     }
	v_lshlrev_b32_e32 v54, 16, v14
	v_and_b32_e32 v55, 0xffff0000, v14
	v_mul_f32_e32 v56, v22, v54
	v_mul_f32_e32 v57, v23, v55
	v_mul_f32_e32 v22, v22, v55
	v_mul_f32_e32 v23, v23, v54
	v_sub_f32_e32 v14, v56, v57
	global_load_dwordx4 v[54:57], v[58:59], off offset:208
	s_nop 0
	global_load_dwordx4 v[58:61], v[58:59], off offset:192
	v_add_f32_e32 v22, v22, v23
	v_cvt_pk_bf16_f32 v144, v14, v22
	v_lshlrev_b32_e32 v14, 16, v15
	v_and_b32_e32 v15, 0xffff0000, v15
	v_mul_f32_e32 v22, v24, v14
	v_mul_f32_e32 v23, v25, v15
	v_pk_mul_f32 v[14:15], v[24:25], v[14:15] op_sel:[0,1] op_sel_hi:[1,0]
	v_sub_f32_e32 v22, v22, v23
	v_add_f32_e32 v14, v14, v15
	v_cvt_pk_bf16_f32 v145, v22, v14
	v_lshlrev_b32_e32 v14, 16, v16
	v_and_b32_e32 v15, 0xffff0000, v16
	v_mul_f32_e32 v22, v18, v14
	v_mul_f32_e32 v23, v19, v15
	v_pk_mul_f32 v[14:15], v[18:19], v[14:15] op_sel:[0,1] op_sel_hi:[1,0]
	v_sub_f32_e32 v16, v22, v23
	v_add_f32_e32 v14, v14, v15
	v_cvt_pk_bf16_f32 v146, v16, v14
	v_lshlrev_b32_e32 v14, 16, v17
	v_and_b32_e32 v15, 0xffff0000, v17
	v_mul_f32_e32 v16, v20, v14
	v_mul_f32_e32 v17, v21, v15
	v_pk_mul_f32 v[14:15], v[20:21], v[14:15] op_sel:[0,1] op_sel_hi:[1,0]
	v_sub_f32_e32 v16, v16, v17
	v_add_f32_e32 v14, v14, v15
	v_cvt_pk_bf16_f32 v147, v16, v14
	v_lshlrev_b32_e32 v14, 16, v26
	v_and_b32_e32 v15, 0xffff0000, v26
	v_mul_f32_e32 v16, v34, v14
	v_mul_f32_e32 v17, v35, v15
	v_pk_mul_f32 v[14:15], v[34:35], v[14:15] op_sel:[0,1] op_sel_hi:[1,0]
	v_sub_f32_e32 v16, v16, v17
	v_add_f32_e32 v14, v14, v15
	v_cvt_pk_bf16_f32 v148, v16, v14
	v_lshlrev_b32_e32 v14, 16, v27
	v_and_b32_e32 v15, 0xffff0000, v27
	v_mul_f32_e32 v16, v36, v14
	v_mul_f32_e32 v17, v37, v15
	v_pk_mul_f32 v[14:15], v[36:37], v[14:15] op_sel:[0,1] op_sel_hi:[1,0]
	v_sub_f32_e32 v16, v16, v17
	v_add_f32_e32 v14, v14, v15
	v_cvt_pk_bf16_f32 v149, v16, v14
	v_lshlrev_b32_e32 v14, 16, v28
	v_and_b32_e32 v15, 0xffff0000, v28
	v_mul_f32_e32 v16, v30, v14
	v_mul_f32_e32 v17, v31, v15
	v_pk_mul_f32 v[14:15], v[30:31], v[14:15] op_sel:[0,1] op_sel_hi:[1,0]
	v_sub_f32_e32 v16, v16, v17
	v_add_f32_e32 v14, v14, v15
	v_cvt_pk_bf16_f32 v150, v16, v14
	v_lshlrev_b32_e32 v14, 16, v29
	v_and_b32_e32 v15, 0xffff0000, v29
	v_mul_f32_e32 v16, v32, v14
	v_mul_f32_e32 v17, v33, v15
	v_pk_mul_f32 v[14:15], v[32:33], v[14:15] op_sel:[0,1] op_sel_hi:[1,0]
	v_sub_f32_e32 v16, v16, v17
	v_add_f32_e32 v14, v14, v15
	v_cvt_pk_bf16_f32 v151, v16, v14
	v_lshlrev_b32_e32 v14, 16, v38
	v_and_b32_e32 v15, 0xffff0000, v38
	v_mul_f32_e32 v16, v46, v14
	v_mul_f32_e32 v17, v47, v15
	v_pk_mul_f32 v[14:15], v[46:47], v[14:15] op_sel:[0,1] op_sel_hi:[1,0]
	v_sub_f32_e32 v16, v16, v17
	v_add_f32_e32 v14, v14, v15
	v_cvt_pk_bf16_f32 v152, v16, v14
	v_lshlrev_b32_e32 v14, 16, v39
	v_and_b32_e32 v15, 0xffff0000, v39
	v_mul_f32_e32 v16, v48, v14
	v_mul_f32_e32 v17, v49, v15
	v_pk_mul_f32 v[14:15], v[48:49], v[14:15] op_sel:[0,1] op_sel_hi:[1,0]
	v_sub_f32_e32 v16, v16, v17
	v_add_f32_e32 v14, v14, v15
	v_cvt_pk_bf16_f32 v153, v16, v14
	v_lshlrev_b32_e32 v14, 16, v40
	v_and_b32_e32 v15, 0xffff0000, v40
	v_mul_f32_e32 v16, v42, v14
	v_mul_f32_e32 v17, v43, v15
	v_pk_mul_f32 v[14:15], v[42:43], v[14:15] op_sel:[0,1] op_sel_hi:[1,0]
	v_sub_f32_e32 v16, v16, v17
	v_add_f32_e32 v14, v14, v15
	v_cvt_pk_bf16_f32 v154, v16, v14
	v_lshlrev_b32_e32 v14, 16, v41
	v_and_b32_e32 v15, 0xffff0000, v41
	v_mul_f32_e32 v16, v44, v14
	v_mul_f32_e32 v17, v45, v15
	v_pk_mul_f32 v[14:15], v[44:45], v[14:15] op_sel:[0,1] op_sel_hi:[1,0]
	v_sub_f32_e32 v16, v16, v17
	v_add_f32_e32 v14, v14, v15
	v_cvt_pk_bf16_f32 v155, v16, v14
	v_lshlrev_b32_e32 v14, 16, v50
	v_and_b32_e32 v15, 0xffff0000, v50
	s_waitcnt vmcnt(0)
	v_mul_f32_e32 v16, v58, v14
	v_mul_f32_e32 v17, v59, v15
	v_pk_mul_f32 v[14:15], v[58:59], v[14:15] op_sel:[0,1] op_sel_hi:[1,0]
	v_sub_f32_e32 v16, v16, v17
	v_add_f32_e32 v14, v14, v15
	v_cvt_pk_bf16_f32 v156, v16, v14
	v_lshlrev_b32_e32 v14, 16, v51
	v_and_b32_e32 v15, 0xffff0000, v51
	v_mul_f32_e32 v16, v60, v14
	v_mul_f32_e32 v17, v61, v15
	v_pk_mul_f32 v[14:15], v[60:61], v[14:15] op_sel:[0,1] op_sel_hi:[1,0]
	v_sub_f32_e32 v16, v16, v17
	v_add_f32_e32 v14, v14, v15
	v_cvt_pk_bf16_f32 v157, v16, v14
	v_lshlrev_b32_e32 v14, 16, v52
	v_and_b32_e32 v15, 0xffff0000, v52
	v_mul_f32_e32 v16, v54, v14
	v_mul_f32_e32 v17, v55, v15
	v_pk_mul_f32 v[14:15], v[54:55], v[14:15] op_sel:[0,1] op_sel_hi:[1,0]
	v_sub_f32_e32 v16, v16, v17
	v_add_f32_e32 v14, v14, v15
	v_cvt_pk_bf16_f32 v158, v16, v14
	v_lshlrev_b32_e32 v14, 16, v53
	v_and_b32_e32 v15, 0xffff0000, v53
	v_mul_f32_e32 v16, v56, v14
	v_mul_f32_e32 v17, v57, v15
	v_pk_mul_f32 v[14:15], v[56:57], v[14:15] op_sel:[0,1] op_sel_hi:[1,0]
	v_sub_f32_e32 v16, v16, v17
	v_add_f32_e32 v14, v14, v15
	v_cvt_pk_bf16_f32 v159, v16, v14
	v_mov_b32_e32 v14, 0x4000
	v_and_or_b32 v187, v9, 8, v14
	v_bitop3_b32 v9, v13, v12, v62 bitop3:0x36
	v_lshlrev_b32_e32 v188, 4, v9
	v_bitop3_b32 v9, v12, v69, 2 bitop3:0x36
	v_lshlrev_b32_e32 v189, 4, v9
	v_bitop3_b32 v9, v12, v69, 4 bitop3:0x36
	v_lshlrev_b32_e32 v190, 4, v9
	v_bitop3_b32 v9, v12, v69, 6 bitop3:0x36
	v_lshlrev_b32_e32 v191, 4, v9
	v_bitop3_b32 v9, v12, v69, 8 bitop3:0x36
	v_lshlrev_b32_e32 v192, 4, v9
	v_bitop3_b32 v9, v12, v69, 10 bitop3:0x36
	v_lshlrev_b32_e32 v193, 4, v9
	v_bitop3_b32 v9, v12, v69, 12 bitop3:0x36
	v_lshlrev_b32_e32 v194, 4, v9
	v_bitop3_b32 v9, v12, v69, 14 bitop3:0x36
	v_lshlrev_b32_e32 v195, 4, v9
	v_bitop3_b32 v9, v63, v12, 7 bitop3:0x6c
	v_lshlrev_b32_e32 v196, 4, v9
	v_bitop3_b32 v9, v12, v11, 2 bitop3:0x36
	v_lshlrev_b32_e32 v197, 4, v9
	v_bitop3_b32 v9, v12, v11, 4 bitop3:0x36
	v_lshlrev_b32_e32 v198, 4, v9
	v_bitop3_b32 v9, v12, v11, 6 bitop3:0x36
	v_lshlrev_b32_e32 v199, 4, v9
	v_and_b32_e32 v9, 12, v8
	v_or_b32_e32 v11, v66, v9
	v_or_b32_e32 v9, v68, v9
	v_lshlrev_b32_e32 v221, 4, v9
	v_bitop3_b32 v9, v8, 4, 12 bitop3:0x6c
	v_lshlrev_b32_e32 v219, 4, v11
	v_bitop3_b32 v11, v64, v9, v12 bitop3:0xde
	v_bitop3_b32 v9, v64, v9, v67 bitop3:0xde
	v_bitop3_b32 v6, v10, 7, v8 bitop3:0x48
	v_lshlrev_b32_e32 v229, 4, v9
	v_bitop3_b32 v9, v8, 8, 12 bitop3:0x6c
	v_lshl_or_b32 v180, v6, 4, v180
	v_or_b32_e32 v6, 4, v0
	v_lshlrev_b32_e32 v228, 4, v11
	v_bitop3_b32 v11, v64, v9, v12 bitop3:0xde
	v_bitop3_b32 v9, v64, v9, v67 bitop3:0xde
	v_mad_u64_u32 v[6:7], s[14:15], v6, s20, 0
	v_lshlrev_b32_e32 v231, 4, v9
	v_bitop3_b32 v9, v8, 12, v8 bitop3:0xc
	s_sext_i32_i8 s14, s12
	v_mov_b32_e32 v8, 0x600000
	v_mad_i64_i32 v[6:7], s[12:13], s14, v8, v[6:7]
	v_lshl_add_u64 v[4:5], v[6:7], 0, v[4:5]
	v_lshl_add_u64 v[182:183], v[4:5], 0, s[0:1]
	v_mad_u64_u32 v[4:5], s[12:13], v0, s20, 0
	v_mad_i64_i32 v[4:5], s[12:13], s14, v8, v[4:5]
	v_or_b32_e32 v65, v176, v62
	s_waitcnt vmcnt(0) lgkmcnt(0)
	s_barrier
; #define WAIT_TILE(all_) do { if (all_) asm volatile("s_waitcnt vmcnt(0) lgkmcnt(0)" ::: "memory"); \
;         else if constexpr (MODE == 0) asm volatile("s_waitcnt vmcnt(5) lgkmcnt(0)" ::: "memory"); else asm volatile("s_waitcnt vmcnt(4) lgkmcnt(0)" ::: "memory"); \
;         __builtin_amdgcn_s_barrier(); asm volatile("" ::: "memory"); } while (0)
; template <int MODE>
; __device__ __forceinline__ void attn_unit(LAS char* lds, const AttnPtrs& A, int b, int qb) {
;     ...
;     f32x16 o1[4];
; #pragma unroll
;     for (int c = 0; c < 4; ++c) o1[c] = f32x16{};
;     float m1 = -1e30f, l1 = 0.f;
;     unsigned long long mw_next = 0ull;
;     if constexpr (MODE == 1) { mw_next = A.MASK[qrow * 64]; asm volatile("" : "+v"(mw_next)); }
;     bf16x8 pk[4]; float a1 = 1.f;
;     ...
;     WAIT_TILE(true);
;     int st_cur = 0, st_nn = 2;
;     for (int t = 0; t < NT; ++t) {
	v_lshlrev_b32_e32 v230, 4, v11
	v_bitop3_b32 v11, v64, v9, v12 bitop3:0xde
	v_bitop3_b32 v9, v64, v9, v67 bitop3:0xde
	v_lshl_add_u64 v[2:3], v[4:5], 0, v[2:3]
	v_mov_b32_e32 v14, v1
	v_mov_b32_e32 v15, v1
	v_lshlrev_b32_e32 v218, 8, v65
	v_lshlrev_b32_e32 v232, 4, v11
	v_lshlrev_b32_e32 v233, 4, v9
	v_lshl_add_u64 v[184:185], v[2:3], 0, s[0:1]
	v_mov_b32_e32 v0, v1
	v_mov_b32_e32 v2, v1
	v_mov_b32_e32 v3, v1
	v_mov_b32_e32 v4, v1
	v_mov_b32_e32 v5, v1
	v_mov_b32_e32 v6, v1
	v_mov_b32_e32 v7, v1
	v_mov_b32_e32 v8, v1
	v_mov_b32_e32 v9, v1
	v_mov_b32_e32 v10, v1
	v_mov_b32_e32 v11, v1
	v_mov_b32_e32 v12, v1
	v_mov_b32_e32 v13, v1
	v_mov_b64_e32 v[30:31], v[14:15]
	v_mov_b64_e32 v[46:47], v[14:15]
	v_mov_b64_e32 v[62:63], v[14:15]
	v_mov_b64_e32 v[78:79], v[14:15]
	v_mov_b32_e32 v179, s53
	v_or_b32_e32 v220, 0x800, v218
	v_or_b32_e32 v222, 0x1000, v218
	v_or_b32_e32 v223, 0x1800, v218
	v_or_b32_e32 v224, 0x2000, v218
	v_or_b32_e32 v225, 0x2800, v218
	v_or_b32_e32 v226, 0x3000, v218
	v_or_b32_e32 v227, 0x3800, v218
	v_mov_b32_e32 v235, 0xf149f2ca
	v_mov_b32_e32 v253, s97
	v_mov_b32_e32 v252, 0
	v_mov_b64_e32 v[236:237], 0
	v_mov_b64_e32 v[238:239], 0
	v_mov_b64_e32 v[240:241], 0
	v_mov_b64_e32 v[242:243], 0
	v_mov_b64_e32 v[244:245], 0
	v_mov_b64_e32 v[246:247], 0
	v_mov_b64_e32 v[248:249], 0
	v_mov_b64_e32 v[250:251], 0
	v_mov_b32_e32 v234, 0
	v_mov_b64_e32 v[28:29], v[12:13]
	v_mov_b64_e32 v[26:27], v[10:11]
	v_mov_b64_e32 v[24:25], v[8:9]
	v_mov_b64_e32 v[22:23], v[6:7]
	v_mov_b64_e32 v[20:21], v[4:5]
	v_mov_b64_e32 v[18:19], v[2:3]
	v_mov_b64_e32 v[16:17], v[0:1]
	v_mov_b64_e32 v[44:45], v[12:13]
	v_mov_b64_e32 v[42:43], v[10:11]
	v_mov_b64_e32 v[40:41], v[8:9]
	v_mov_b64_e32 v[38:39], v[6:7]
	v_mov_b64_e32 v[36:37], v[4:5]
	v_mov_b64_e32 v[34:35], v[2:3]
	v_mov_b64_e32 v[32:33], v[0:1]
	v_mov_b64_e32 v[60:61], v[12:13]
	v_mov_b64_e32 v[58:59], v[10:11]
	v_mov_b64_e32 v[56:57], v[8:9]
	v_mov_b64_e32 v[54:55], v[6:7]
	v_mov_b64_e32 v[52:53], v[4:5]
	v_mov_b64_e32 v[50:51], v[2:3]
	v_mov_b64_e32 v[48:49], v[0:1]
	v_mov_b64_e32 v[76:77], v[12:13]
	v_mov_b64_e32 v[74:75], v[10:11]
	v_mov_b64_e32 v[72:73], v[8:9]
	v_mov_b64_e32 v[70:71], v[6:7]
	v_mov_b64_e32 v[68:69], v[4:5]
	v_mov_b64_e32 v[66:67], v[2:3]
	v_mov_b64_e32 v[64:65], v[0:1]
	s_mov_b32 s14, 0
	.p2align	6

; template <class Epi, class Sched, bool ALIGN_EPI = false, bool SP2 = false>
; __device__ __forceinline__ void gemm_phase(PG8_LAS unsigned char* lds, const Gemm g, const Sched& S, const Epi& E) {
;     ...
;         const bool has_next = S.next(ui + 1, nxt);
;         const char* nA = has_next ? (const char*)g.A + (size_t)nxt.pm * tstep : cA; const char* nB = has_next ? (const char*)g.Bt + (size_t)nxt.pn * tstep : cB;
;         for (int t = 0; t < nt; t += 2) {
;             const bool last = (t == nt - 2);
;             const char* a1 = cA + (size_t)(t + 1) * kstep;
;             const char* a2 = last ? nA : cA + (size_t)(t + 2) * kstep; const char* b2 = last ? nB : cB + (size_t)(t + 2) * kstep;
;             const char* a3 = a2 + kstep; const char* b3 = b2 + kstep;
;     ...
; #pragma unroll
;         for (int a = 0; a < 2; ++a)
; #pragma unroll
;             for (int b = 0; b < 2; ++b)
; #pragma unroll
;                 for (int m = 0; m < 4; ++m)
; #pragma unroll
;                     for (int n = 0; n < 2; ++n) acc[a][b][m][n] = (f32x4){0.f, 0.f, 0.f, 0.f};
.LBB0_1269:
	s_ashr_i32 s13, s12, 31
	s_lshl_b64 s[14:15], s[12:13], 20
	s_add_u32 s14, s21, s14
	s_addc_u32 s15, s26, s15
	s_and_b64 s[16:17], s[2:3], exec
	s_cselect_b32 s13, s15, s23
	s_cselect_b32 s50, s14, s22
	s_ashr_i32 s11, s10, 31
	s_lshl_b64 s[16:17], s[10:11], 20
	s_add_u32 s16, s27, s16
	s_addc_u32 s17, s28, s17
	s_and_b64 s[24:25], s[2:3], exec
	s_cselect_b32 s11, s17, s19
	s_cselect_b32 s51, s16, s18
	s_add_u32 s52, s18, 0x100
	s_addc_u32 s53, s19, 0
	s_add_u32 s18, s22, 0x80080
	v_mov_b32_e32 v2, 0
	s_addc_u32 s19, s23, 0
	s_mov_b32 s54, -2
	v_mov_b32_e32 v3, v2
	v_mov_b32_e32 v4, v2
	v_mov_b32_e32 v5, v2
	v_mov_b32_e32 v6, v2
	v_mov_b32_e32 v7, v2
	v_mov_b32_e32 v8, v2
	v_mov_b32_e32 v9, v2
	v_mov_b32_e32 v10, v2
	v_mov_b32_e32 v11, v2
	v_mov_b32_e32 v12, v2
	v_mov_b32_e32 v13, v2
	v_mov_b32_e32 v14, v2
	v_mov_b32_e32 v15, v2
	v_mov_b32_e32 v16, v2
	v_mov_b32_e32 v17, v2
	v_mov_b32_e32 v18, v2
	v_mov_b32_e32 v19, v2
	v_mov_b32_e32 v20, v2
	v_mov_b32_e32 v21, v2
	v_mov_b32_e32 v22, v2
	v_mov_b32_e32 v23, v2
	v_mov_b32_e32 v24, v2
	v_mov_b32_e32 v25, v2
	v_mov_b32_e32 v26, v2
	v_mov_b32_e32 v27, v2
	v_mov_b32_e32 v28, v2
	v_mov_b32_e32 v29, v2
	v_mov_b32_e32 v30, v2
	v_mov_b32_e32 v31, v2
	v_mov_b32_e32 v32, v2
	v_mov_b32_e32 v33, v2
	v_mov_b32_e32 v66, v2
	v_mov_b32_e32 v67, v2
	v_mov_b32_e32 v68, v2
	v_mov_b32_e32 v69, v2
	v_mov_b32_e32 v70, v2
	v_mov_b32_e32 v71, v2
	v_mov_b32_e32 v72, v2
	v_mov_b32_e32 v73, v2
	v_mov_b32_e32 v74, v2
	v_mov_b32_e32 v75, v2
	v_mov_b32_e32 v76, v2
	v_mov_b32_e32 v77, v2
	v_mov_b32_e32 v78, v2
	v_mov_b32_e32 v79, v2
	v_mov_b32_e32 v80, v2
	v_mov_b32_e32 v81, v2
	v_mov_b32_e32 v82, v2
	v_mov_b32_e32 v83, v2
	v_mov_b32_e32 v84, v2
	v_mov_b32_e32 v85, v2
	v_mov_b32_e32 v86, v2
	v_mov_b32_e32 v87, v2
	v_mov_b32_e32 v88, v2
	v_mov_b32_e32 v89, v2
	v_mov_b32_e32 v90, v2
	v_mov_b32_e32 v91, v2
	v_mov_b32_e32 v92, v2
	v_mov_b32_e32 v93, v2
	v_mov_b32_e32 v94, v2
	v_mov_b32_e32 v95, v2
	v_mov_b32_e32 v96, v2
	v_mov_b32_e32 v97, v2
	v_mov_b32_e32 v34, v2
	v_mov_b32_e32 v35, v2
	v_mov_b32_e32 v36, v2
	v_mov_b32_e32 v37, v2
	v_mov_b32_e32 v38, v2
	v_mov_b32_e32 v39, v2
	v_mov_b32_e32 v40, v2
	v_mov_b32_e32 v41, v2
	v_mov_b32_e32 v42, v2
	v_mov_b32_e32 v43, v2
	v_mov_b32_e32 v44, v2
	v_mov_b32_e32 v45, v2
	v_mov_b32_e32 v46, v2
	v_mov_b32_e32 v47, v2
	v_mov_b32_e32 v48, v2
	v_mov_b32_e32 v49, v2
	v_mov_b32_e32 v50, v2
	v_mov_b32_e32 v51, v2
	v_mov_b32_e32 v52, v2
	v_mov_b32_e32 v53, v2
	v_mov_b32_e32 v54, v2
	v_mov_b32_e32 v55, v2
	v_mov_b32_e32 v56, v2
	v_mov_b32_e32 v57, v2
	v_mov_b32_e32 v58, v2
	v_mov_b32_e32 v59, v2
	v_mov_b32_e32 v60, v2
	v_mov_b32_e32 v61, v2
	v_mov_b32_e32 v62, v2
	v_mov_b32_e32 v63, v2
	v_mov_b32_e32 v64, v2
	v_mov_b32_e32 v65, v2
	v_mov_b32_e32 v98, v2
	v_mov_b32_e32 v99, v2
	v_mov_b32_e32 v100, v2
	v_mov_b32_e32 v101, v2
	v_mov_b32_e32 v102, v2
	v_mov_b32_e32 v103, v2
	v_mov_b32_e32 v104, v2
	v_mov_b32_e32 v105, v2
	v_mov_b32_e32 v106, v2
	v_mov_b32_e32 v107, v2
	v_mov_b32_e32 v108, v2
	v_mov_b32_e32 v109, v2
	v_mov_b32_e32 v110, v2
	v_mov_b32_e32 v111, v2
	v_mov_b32_e32 v112, v2
	v_mov_b32_e32 v113, v2
	v_mov_b32_e32 v114, v2
	v_mov_b32_e32 v115, v2
	v_mov_b32_e32 v116, v2
	v_mov_b32_e32 v117, v2
	v_mov_b32_e32 v118, v2
	v_mov_b32_e32 v119, v2
	v_mov_b32_e32 v120, v2
	v_mov_b32_e32 v121, v2
	v_mov_b32_e32 v122, v2
	v_mov_b32_e32 v123, v2
	v_mov_b32_e32 v124, v2
	v_mov_b32_e32 v125, v2
	v_mov_b32_e32 v126, v2
	v_mov_b32_e32 v127, v2
	v_mov_b32_e32 v128, v2
	v_mov_b32_e32 v129, v2
	.p2align	6

; template <class Epi, class Sched, bool ALIGN_EPI = false, bool SP2 = false>
; __device__ __forceinline__ void gemm_phase(PG8_LAS unsigned char* lds, const Gemm g, const Sched& S, const Epi& E) {
;     ...
;         const bool has_next = S.next(ui + 1, nxt);
;         const char* nA = has_next ? (const char*)g.A + (size_t)nxt.pm * tstep : cA; const char* nB = has_next ? (const char*)g.Bt + (size_t)nxt.pn * tstep : cB;
;         for (int t = 0; t < nt; t += 2) {
;             const bool last = (t == nt - 2);
;             const char* a1 = cA + (size_t)(t + 1) * kstep;
;             const char* a2 = last ? nA : cA + (size_t)(t + 2) * kstep; const char* b2 = last ? nB : cB + (size_t)(t + 2) * kstep;
;             const char* a3 = a2 + kstep; const char* b3 = b2 + kstep;
;     ...
; #pragma unroll
;         for (int a = 0; a < 2; ++a)
; #pragma unroll
;             for (int b = 0; b < 2; ++b)
; #pragma unroll
;                 for (int m = 0; m < 4; ++m)
; #pragma unroll
;                     for (int n = 0; n < 2; ++n) acc[a][b][m][n] = (f32x4){0.f, 0.f, 0.f, 0.f};
.LBB0_1341:
	s_ashr_i32 s17, s16, 31
	s_lshl_b64 s[18:19], s[16:17], 20
	s_add_u32 s18, s0, s18
	s_addc_u32 s19, s1, s19
	s_and_b64 s[22:23], s[2:3], exec
	s_cselect_b32 s17, s19, s25
	s_cselect_b32 s52, s18, s24
	s_ashr_i32 s15, s14, 31
	s_lshl_b64 s[22:23], s[14:15], 20
	s_add_u32 s22, s21, s22
	s_addc_u32 s23, s28, s23
	s_and_b64 s[26:27], s[2:3], exec
	s_cselect_b32 s15, s23, s5
	s_cselect_b32 s53, s22, s4
	s_add_u32 s54, s4, 0x100
	s_addc_u32 s55, s5, 0
	s_add_u32 s4, s24, 0x80080
	v_mov_b32_e32 v2, 0
	s_addc_u32 s5, s25, 0
	s_mov_b32 s56, -2
	v_mov_b32_e32 v3, v2
	v_mov_b32_e32 v4, v2
	v_mov_b32_e32 v5, v2
	v_mov_b32_e32 v6, v2
	v_mov_b32_e32 v7, v2
	v_mov_b32_e32 v8, v2
	v_mov_b32_e32 v9, v2
	v_mov_b32_e32 v10, v2
	v_mov_b32_e32 v11, v2
	v_mov_b32_e32 v12, v2
	v_mov_b32_e32 v13, v2
	v_mov_b32_e32 v14, v2
	v_mov_b32_e32 v15, v2
	v_mov_b32_e32 v16, v2
	v_mov_b32_e32 v17, v2
	v_mov_b32_e32 v18, v2
	v_mov_b32_e32 v19, v2
	v_mov_b32_e32 v20, v2
	v_mov_b32_e32 v21, v2
	v_mov_b32_e32 v22, v2
	v_mov_b32_e32 v23, v2
	v_mov_b32_e32 v24, v2
	v_mov_b32_e32 v25, v2
	v_mov_b32_e32 v26, v2
	v_mov_b32_e32 v27, v2
	v_mov_b32_e32 v28, v2
	v_mov_b32_e32 v29, v2
	v_mov_b32_e32 v30, v2
	v_mov_b32_e32 v31, v2
	v_mov_b32_e32 v32, v2
	v_mov_b32_e32 v33, v2
	v_mov_b32_e32 v34, v2
	v_mov_b32_e32 v35, v2
	v_mov_b32_e32 v36, v2
	v_mov_b32_e32 v37, v2
	v_mov_b32_e32 v38, v2
	v_mov_b32_e32 v39, v2
	v_mov_b32_e32 v40, v2
	v_mov_b32_e32 v41, v2
	v_mov_b32_e32 v42, v2
	v_mov_b32_e32 v43, v2
	v_mov_b32_e32 v44, v2
	v_mov_b32_e32 v45, v2
	v_mov_b32_e32 v46, v2
	v_mov_b32_e32 v47, v2
	v_mov_b32_e32 v48, v2
	v_mov_b32_e32 v49, v2
	v_mov_b32_e32 v50, v2
	v_mov_b32_e32 v51, v2
	v_mov_b32_e32 v52, v2
	v_mov_b32_e32 v53, v2
	v_mov_b32_e32 v54, v2
	v_mov_b32_e32 v55, v2
	v_mov_b32_e32 v56, v2
	v_mov_b32_e32 v57, v2
	v_mov_b32_e32 v58, v2
	v_mov_b32_e32 v59, v2
	v_mov_b32_e32 v60, v2
	v_mov_b32_e32 v61, v2
	v_mov_b32_e32 v62, v2
	v_mov_b32_e32 v63, v2
	v_mov_b32_e32 v64, v2
	v_mov_b32_e32 v65, v2
	v_mov_b32_e32 v66, v2
	v_mov_b32_e32 v67, v2
	v_mov_b32_e32 v68, v2
	v_mov_b32_e32 v69, v2
	v_mov_b32_e32 v70, v2
	v_mov_b32_e32 v71, v2
	v_mov_b32_e32 v72, v2
	v_mov_b32_e32 v73, v2
	v_mov_b32_e32 v74, v2
	v_mov_b32_e32 v75, v2
	v_mov_b32_e32 v76, v2
	v_mov_b32_e32 v77, v2
	v_mov_b32_e32 v78, v2
	v_mov_b32_e32 v79, v2
	v_mov_b32_e32 v80, v2
	v_mov_b32_e32 v81, v2
	v_mov_b32_e32 v82, v2
	v_mov_b32_e32 v83, v2
	v_mov_b32_e32 v84, v2
	v_mov_b32_e32 v85, v2
	v_mov_b32_e32 v86, v2
	v_mov_b32_e32 v87, v2
	v_mov_b32_e32 v88, v2
	v_mov_b32_e32 v89, v2
	v_mov_b32_e32 v90, v2
	v_mov_b32_e32 v91, v2
	v_mov_b32_e32 v92, v2
	v_mov_b32_e32 v93, v2
	v_mov_b32_e32 v94, v2
	v_mov_b32_e32 v95, v2
	v_mov_b32_e32 v96, v2
	v_mov_b32_e32 v97, v2
	v_mov_b32_e32 v98, v2
	v_mov_b32_e32 v99, v2
	v_mov_b32_e32 v100, v2
	v_mov_b32_e32 v101, v2
	v_mov_b32_e32 v102, v2
	v_mov_b32_e32 v103, v2
	v_mov_b32_e32 v104, v2
	v_mov_b32_e32 v105, v2
	v_mov_b32_e32 v106, v2
	v_mov_b32_e32 v107, v2
	v_mov_b32_e32 v108, v2
	v_mov_b32_e32 v109, v2
	v_mov_b32_e32 v110, v2
	v_mov_b32_e32 v111, v2
	v_mov_b32_e32 v112, v2
	v_mov_b32_e32 v113, v2
	v_mov_b32_e32 v114, v2
	v_mov_b32_e32 v115, v2
	v_mov_b32_e32 v116, v2
	v_mov_b32_e32 v117, v2
	v_mov_b32_e32 v118, v2
	v_mov_b32_e32 v119, v2
	v_mov_b32_e32 v120, v2
	v_mov_b32_e32 v121, v2
	v_mov_b32_e32 v122, v2
	v_mov_b32_e32 v123, v2
	v_mov_b32_e32 v124, v2
	v_mov_b32_e32 v125, v2
	v_mov_b32_e32 v126, v2
	v_mov_b32_e32 v127, v2
	v_mov_b32_e32 v128, v2
	v_mov_b32_e32 v129, v2
	.p2align	6
